# MLA loop 2nd key half: exp/rowsum/pack interleaved with the 8 P.V MFMAs (was VALU block then bare MFMAs); stagger afterX
# baseline (speedup 1.0000x reference)
.LBB0_527:
	ds_read_b64_tr_b16 v[68:69], v214 offset:28672
	ds_read_b64_tr_b16 v[70:71], v214 offset:29184
	ds_read_b64_tr_b16 v[158:159], v214 offset:36864
	ds_read_b64_tr_b16 v[160:161], v214 offset:37376
	ds_read_b64_tr_b16 v[72:73], v214 offset:29696
	ds_read_b64_tr_b16 v[74:75], v214 offset:30208
	ds_read_b64_tr_b16 v[162:163], v214 offset:37888
	ds_read_b64_tr_b16 v[164:165], v214 offset:38400
	ds_read_b64_tr_b16 v[76:77], v214 offset:30720
	ds_read_b64_tr_b16 v[78:79], v214 offset:31232
	ds_read_b64_tr_b16 v[166:167], v214 offset:38912
	ds_read_b64_tr_b16 v[168:169], v214 offset:39424
	ds_read_b64_tr_b16 v[98:99], v214 offset:31744
	ds_read_b64_tr_b16 v[100:101], v214 offset:32256
	ds_read_b64_tr_b16 v[170:171], v214 offset:39936
	ds_read_b64_tr_b16 v[172:173], v214 offset:40448
	s_add_i32 s13, s13, 1
	v_exp_f32_e32 v50, v50
	v_exp_f32_e32 v51, v51
	v_exp_f32_e32 v52, v52
	v_exp_f32_e32 v53, v53
	v_exp_f32_e32 v54, v54
	v_exp_f32_e32 v55, v55
	v_exp_f32_e32 v56, v56
	v_exp_f32_e32 v57, v57
	v_pk_add_f32 v[174:175], v[50:51], v[52:53]
	v_pk_add_f32 v[174:175], v[174:175], v[54:55]
	v_pk_add_f32 v[174:175], v[174:175], v[56:57]
	v_cvt_pk_bf16_f32 v50, v50, v51
	v_cvt_pk_bf16_f32 v51, v52, v53
	v_cvt_pk_bf16_f32 v52, v54, v55
	v_cvt_pk_bf16_f32 v53, v56, v57
	v_exp_f32_e32 v58, v58
	v_exp_f32_e32 v59, v59
	s_waitcnt lgkmcnt(12)
	v_mfma_f32_32x32x16_bf16 v[2:17], v[68:71], v[50:53], v[2:17]
	v_exp_f32_e32 v60, v60
	v_exp_f32_e32 v61, v61
	v_exp_f32_e32 v62, v62
	v_mfma_f32_32x32x16_bf16 v[18:33], v[158:161], v[50:53], v[18:33]
	v_exp_f32_e32 v63, v63
	v_exp_f32_e32 v64, v64
	v_exp_f32_e32 v65, v65
	v_pk_add_f32 v[174:175], v[174:175], v[58:59]
	v_pk_add_f32 v[174:175], v[174:175], v[60:61]
	v_pk_add_f32 v[174:175], v[174:175], v[62:63]
	v_pk_add_f32 v[174:175], v[174:175], v[64:65]
	v_cvt_pk_bf16_f32 v54, v58, v59
	v_cvt_pk_bf16_f32 v55, v60, v61
	v_cvt_pk_bf16_f32 v56, v62, v63
	v_cvt_pk_bf16_f32 v57, v64, v65
	v_exp_f32_e32 v82, v82
	v_exp_f32_e32 v83, v83
	s_waitcnt lgkmcnt(8)
	v_mfma_f32_32x32x16_bf16 v[2:17], v[72:75], v[54:57], v[2:17]
	v_exp_f32_e32 v84, v84
	v_exp_f32_e32 v85, v85
	v_exp_f32_e32 v86, v86
	v_mfma_f32_32x32x16_bf16 v[18:33], v[162:165], v[54:57], v[18:33]
	v_exp_f32_e32 v87, v87
	v_exp_f32_e32 v88, v88
	v_exp_f32_e32 v89, v89
	v_pk_add_f32 v[176:177], v[82:83], v[84:85]
	v_pk_add_f32 v[176:177], v[176:177], v[86:87]
	v_pk_add_f32 v[176:177], v[176:177], v[88:89]
	v_cvt_pk_bf16_f32 v58, v82, v83
	v_cvt_pk_bf16_f32 v59, v84, v85
	v_cvt_pk_bf16_f32 v60, v86, v87
	v_cvt_pk_bf16_f32 v61, v88, v89
	v_exp_f32_e32 v90, v90
	v_exp_f32_e32 v91, v91
	s_waitcnt lgkmcnt(4)
	v_mfma_f32_32x32x16_bf16 v[2:17], v[76:79], v[58:61], v[2:17]
	v_exp_f32_e32 v92, v92
	v_exp_f32_e32 v93, v93
	v_exp_f32_e32 v94, v94
	v_mfma_f32_32x32x16_bf16 v[18:33], v[166:169], v[58:61], v[18:33]
	v_exp_f32_e32 v95, v95
	v_exp_f32_e32 v96, v96
	v_exp_f32_e32 v97, v97
	v_pk_add_f32 v[176:177], v[176:177], v[90:91]
	v_pk_add_f32 v[176:177], v[176:177], v[92:93]
	v_pk_add_f32 v[176:177], v[176:177], v[94:95]
	v_pk_add_f32 v[176:177], v[176:177], v[96:97]
	v_cvt_pk_bf16_f32 v62, v90, v91
	v_cvt_pk_bf16_f32 v63, v92, v93
	v_cvt_pk_bf16_f32 v64, v94, v95
	v_cvt_pk_bf16_f32 v65, v96, v97
	v_pk_add_f32 v[174:175], v[174:175], v[176:177]
	s_add_i32 s0, s75, 0xa000
	s_cmp_lt_i32 s75, 0x14000
	s_cselect_b32 s75, s0, 0
	s_addk_i32 s38, 0x80
	v_add_f32_e32 v176, v174, v175
	s_waitcnt lgkmcnt(0)
	v_mfma_f32_32x32x16_bf16 v[2:17], v[98:101], v[62:65], v[2:17]
	v_add_f32_e32 v231, v66, v176
	s_cmp_lg_u32 s13, 16
	v_mfma_f32_32x32x16_bf16 v[18:33], v[170:173], v[62:65], v[18:33]
	s_cbranch_scc0 .LBB0_517
